# Merged-V attention: second-half V fragment reads hoisted to the start of the P.V phase; steady-state closing wait vmcnt(3)
# speedup vs baseline: 1.0505x; 1.0068x over previous
.LBB0_238:
	s_waitcnt lgkmcnt(14)
	v_add_u32_e32 v15, s98, v220
	v_add_u32_e32 v15, 0xf000, v15
	ds_read_b64_tr_b16 v[68:69], v15 offset:24576
	ds_read_b64_tr_b16 v[70:71], v15 offset:25088
	ds_read_b64_tr_b16 v[72:73], v15 offset:28672
	ds_read_b64_tr_b16 v[74:75], v15 offset:29184
	ds_read_b64_tr_b16 v[76:77], v15 offset:25600
	ds_read_b64_tr_b16 v[78:79], v15 offset:26112
	ds_read_b64_tr_b16 v[88:89], v15 offset:29696
	ds_read_b64_tr_b16 v[90:91], v15 offset:30208
	ds_read_b64_tr_b16 v[92:93], v15 offset:26624
	ds_read_b64_tr_b16 v[94:95], v15 offset:27136
	ds_read_b64_tr_b16 v[164:165], v15 offset:30720
	ds_read_b64_tr_b16 v[166:167], v15 offset:31232
	ds_read_b64_tr_b16 v[168:169], v15 offset:27648
	ds_read_b64_tr_b16 v[170:171], v15 offset:28160
	v_mfma_f32_32x32x16_bf16 v[32:47], v[156:159], v[192:195], v[32:47]
	v_exp_f32_e32 v112, v112
	v_exp_f32_e32 v113, v113
	v_exp_f32_e32 v114, v114
	v_exp_f32_e32 v115, v115
	s_waitcnt lgkmcnt(12)
	v_mfma_f32_32x32x16_bf16 v[16:31], v[156:159], v[188:191], v[16:31]
	v_exp_f32_e32 v116, v116
	v_exp_f32_e32 v117, v117
	v_exp_f32_e32 v118, v118
	v_exp_f32_e32 v119, v119
	v_add_u32_e32 v0, s45, v219
	ds_read_b128 v[64:67], v0
	ds_read_b128 v[160:163], v0 offset:512
	s_waitcnt lgkmcnt(12)
	v_mfma_f32_32x32x16_bf16 v[32:47], v[152:155], v[184:187], v[32:47]
	v_exp_f32_e32 v120, v120
	v_exp_f32_e32 v121, v121
	v_exp_f32_e32 v122, v122
	v_exp_f32_e32 v123, v123
	ds_read_b128 v[192:195], v0 offset:2048
	ds_read_b128 v[184:187], v0 offset:2560
	s_waitcnt lgkmcnt(12)
	v_mfma_f32_32x32x16_bf16 v[16:31], v[152:155], v[84:87], v[16:31]
	v_exp_f32_e32 v124, v124
	v_exp_f32_e32 v125, v125
	v_exp_f32_e32 v126, v126
	v_exp_f32_e32 v127, v127
	ds_read_b128 v[188:191], v0 offset:4096
	ds_read_b128 v[176:179], v0 offset:4608
	s_waitcnt lgkmcnt(12)
	v_mfma_f32_32x32x16_bf16 v[32:47], v[148:151], v[80:83], v[32:47]
	v_exp_f32_e32 v96, v96
	v_exp_f32_e32 v97, v97
	v_exp_f32_e32 v98, v98
	v_exp_f32_e32 v99, v99
	ds_read_b128 v[180:183], v0 offset:6144
	ds_read_b128 v[172:175], v0 offset:6656
	s_waitcnt lgkmcnt(12)
	v_mfma_f32_32x32x16_bf16 v[16:31], v[148:151], v[10:13], v[16:31]
	v_exp_f32_e32 v100, v100
	v_exp_f32_e32 v101, v101
	v_exp_f32_e32 v102, v102
	v_exp_f32_e32 v103, v103
	s_waitcnt lgkmcnt(10)
	v_mfma_f32_32x32x16_bf16 v[32:47], v[140:143], v[6:9], v[32:47]
	v_exp_f32_e32 v104, v104
	v_exp_f32_e32 v105, v105
	v_exp_f32_e32 v106, v106
	v_exp_f32_e32 v107, v107
	s_waitcnt lgkmcnt(8)
	v_mfma_f32_32x32x16_bf16 v[16:31], v[140:143], v[2:5], v[16:31]
	ds_read_b64_tr_b16 v[2:3], v15 offset:31744
	ds_read_b64_tr_b16 v[4:5], v15 offset:32256
	s_waitcnt lgkmcnt(2)
	v_mfma_f32_32x32x16_bf16 v[224:239], v[156:159], v[68:71], v[224:239]
	v_mfma_f32_32x32x16_bf16 v[240:255], v[156:159], v[72:75], v[240:255]
	v_mfma_f32_32x32x16_bf16 v[224:239], v[152:155], v[76:79], v[224:239]
	v_mfma_f32_32x32x16_bf16 v[240:255], v[152:155], v[88:91], v[240:255]
	v_mfma_f32_32x32x16_bf16 v[224:239], v[148:151], v[92:95], v[224:239]
	v_mfma_f32_32x32x16_bf16 v[240:255], v[148:151], v[164:167], v[240:255]
	v_mfma_f32_32x32x16_bf16 v[224:239], v[140:143], v[168:171], v[224:239]
	s_waitcnt lgkmcnt(0)
	v_mfma_f32_32x32x16_bf16 v[240:255], v[140:143], v[2:5], v[240:255]
	v_exp_f32_e32 v108, v108
	v_exp_f32_e32 v109, v109
	v_exp_f32_e32 v110, v110
	v_exp_f32_e32 v111, v111
	s_waitcnt vmcnt(3) lgkmcnt(0)
	s_barrier
	s_andn2_b64 vcc, exec, s[2:3]
	v_add_u32_e32 v0, s60, v221
	s_cbranch_vccnz .LBB0_240
	s_waitcnt lgkmcnt(0)
	ds_read_b128 v[2:5], v0 offset:49248
	ds_read_b128 v[6:9], v0 offset:49216
	ds_read_b128 v[10:13], v0 offset:49184
	ds_read_b128 v[68:71], v0 offset:49152
	s_waitcnt lgkmcnt(3)
	v_pk_mul_f32 v[44:45], v[44:45], v[2:3]
	v_pk_mul_f32 v[236:237], v[236:237], v[2:3]
	s_waitcnt lgkmcnt(2)
	v_pk_mul_f32 v[40:41], v[40:41], v[6:7]
	v_pk_mul_f32 v[232:233], v[232:233], v[6:7]
	s_waitcnt lgkmcnt(1)
	v_pk_mul_f32 v[36:37], v[36:37], v[10:11]
	v_pk_mul_f32 v[228:229], v[228:229], v[10:11]
	v_pk_mul_f32 v[46:47], v[46:47], v[4:5]
	v_pk_mul_f32 v[238:239], v[238:239], v[4:5]
	v_pk_mul_f32 v[42:43], v[42:43], v[8:9]
	v_pk_mul_f32 v[234:235], v[234:235], v[8:9]
	v_pk_mul_f32 v[38:39], v[38:39], v[12:13]
	v_pk_mul_f32 v[230:231], v[230:231], v[12:13]
	s_waitcnt lgkmcnt(0)
	v_pk_mul_f32 v[34:35], v[34:35], v[70:71]
	v_pk_mul_f32 v[226:227], v[226:227], v[70:71]
	v_pk_mul_f32 v[32:33], v[32:33], v[68:69]
	v_pk_mul_f32 v[224:225], v[224:225], v[68:69]
	v_pk_mul_f32 v[28:29], v[28:29], v[2:3]
	v_pk_mul_f32 v[252:253], v[252:253], v[2:3]
	v_pk_mul_f32 v[24:25], v[24:25], v[6:7]
	v_pk_mul_f32 v[248:249], v[248:249], v[6:7]
	v_pk_mul_f32 v[20:21], v[20:21], v[10:11]
	v_pk_mul_f32 v[244:245], v[244:245], v[10:11]
	v_pk_mul_f32 v[30:31], v[30:31], v[4:5]
	v_pk_mul_f32 v[254:255], v[254:255], v[4:5]
	v_pk_mul_f32 v[26:27], v[26:27], v[8:9]
	v_pk_mul_f32 v[250:251], v[250:251], v[8:9]
	v_pk_mul_f32 v[22:23], v[22:23], v[12:13]
	v_pk_mul_f32 v[246:247], v[246:247], v[12:13]
	v_pk_mul_f32 v[18:19], v[18:19], v[70:71]
	v_pk_mul_f32 v[242:243], v[242:243], v[70:71]
	v_pk_mul_f32 v[16:17], v[16:17], v[68:69]
	v_pk_mul_f32 v[240:241], v[240:241], v[68:69]

.LBB0_241:
	s_waitcnt lgkmcnt(14)
	v_add_u32_e32 v15, s98, v220
	v_add_u32_e32 v15, 0xf000, v15
	ds_read_b64_tr_b16 v[96:97], v15 offset:24576
	ds_read_b64_tr_b16 v[98:99], v15 offset:25088
	ds_read_b64_tr_b16 v[100:101], v15 offset:28672
	ds_read_b64_tr_b16 v[102:103], v15 offset:29184
	ds_read_b64_tr_b16 v[104:105], v15 offset:25600
	ds_read_b64_tr_b16 v[106:107], v15 offset:26112
	ds_read_b64_tr_b16 v[108:109], v15 offset:29696
	ds_read_b64_tr_b16 v[110:111], v15 offset:30208
	ds_read_b64_tr_b16 v[120:121], v15 offset:26624
	ds_read_b64_tr_b16 v[122:123], v15 offset:27136
	ds_read_b64_tr_b16 v[124:125], v15 offset:30720
	ds_read_b64_tr_b16 v[126:127], v15 offset:31232
	ds_read_b64_tr_b16 v[192:193], v15 offset:27648
	ds_read_b64_tr_b16 v[194:195], v15 offset:28160
	v_mfma_f32_32x32x16_bf16 v[32:47], v[156:159], v[168:171], v[32:47]
	v_exp_f32_e32 v80, v80
	v_exp_f32_e32 v81, v81
	v_exp_f32_e32 v82, v82
	v_exp_f32_e32 v83, v83
	s_waitcnt lgkmcnt(12)
	v_mfma_f32_32x32x16_bf16 v[16:31], v[156:159], v[164:167], v[16:31]
	v_exp_f32_e32 v84, v84
	v_exp_f32_e32 v85, v85
	v_exp_f32_e32 v86, v86
	v_exp_f32_e32 v87, v87
	v_add_u32_e32 v14, s64, v219
	ds_read_b128 v[188:191], v14
	ds_read_b128 v[184:187], v14 offset:512
	s_waitcnt lgkmcnt(12)
	v_mfma_f32_32x32x16_bf16 v[32:47], v[152:155], v[160:163], v[32:47]
	v_exp_f32_e32 v88, v88
	v_exp_f32_e32 v89, v89
	v_exp_f32_e32 v90, v90
	v_exp_f32_e32 v91, v91
	ds_read_b128 v[180:183], v14 offset:2048
	ds_read_b128 v[176:179], v14 offset:2560
	s_waitcnt lgkmcnt(12)
	v_mfma_f32_32x32x16_bf16 v[16:31], v[152:155], v[116:119], v[16:31]
	v_exp_f32_e32 v92, v92
	v_exp_f32_e32 v93, v93
	v_exp_f32_e32 v94, v94
	v_exp_f32_e32 v95, v95
	ds_read_b128 v[172:175], v14 offset:4096
	ds_read_b128 v[168:171], v14 offset:4608
	s_waitcnt lgkmcnt(12)
	v_mfma_f32_32x32x16_bf16 v[32:47], v[148:151], v[112:115], v[32:47]
	v_exp_f32_e32 v64, v64
	v_exp_f32_e32 v65, v65
	v_exp_f32_e32 v66, v66
	v_exp_f32_e32 v67, v67
	ds_read_b128 v[164:167], v14 offset:6144
	ds_read_b128 v[160:163], v14 offset:6656
	s_waitcnt lgkmcnt(12)
	v_mfma_f32_32x32x16_bf16 v[16:31], v[148:151], v[10:13], v[16:31]
	v_exp_f32_e32 v68, v68
	v_exp_f32_e32 v69, v69
	v_exp_f32_e32 v70, v70
	v_exp_f32_e32 v71, v71
	s_waitcnt lgkmcnt(10)
	v_mfma_f32_32x32x16_bf16 v[32:47], v[140:143], v[6:9], v[32:47]
	v_exp_f32_e32 v72, v72
	v_exp_f32_e32 v73, v73
	v_exp_f32_e32 v74, v74
	v_exp_f32_e32 v75, v75
	s_waitcnt lgkmcnt(8)
	v_mfma_f32_32x32x16_bf16 v[16:31], v[140:143], v[2:5], v[16:31]
	ds_read_b64_tr_b16 v[2:3], v15 offset:31744
	ds_read_b64_tr_b16 v[4:5], v15 offset:32256
	s_waitcnt lgkmcnt(2)
	v_mfma_f32_32x32x16_bf16 v[224:239], v[156:159], v[96:99], v[224:239]
	v_mfma_f32_32x32x16_bf16 v[240:255], v[156:159], v[100:103], v[240:255]
	v_mfma_f32_32x32x16_bf16 v[224:239], v[152:155], v[104:107], v[224:239]
	v_mfma_f32_32x32x16_bf16 v[240:255], v[152:155], v[108:111], v[240:255]
	v_mfma_f32_32x32x16_bf16 v[224:239], v[148:151], v[120:123], v[224:239]
	v_mfma_f32_32x32x16_bf16 v[240:255], v[148:151], v[124:127], v[240:255]
	v_mfma_f32_32x32x16_bf16 v[224:239], v[140:143], v[192:195], v[224:239]
	s_waitcnt lgkmcnt(0)
	v_mfma_f32_32x32x16_bf16 v[240:255], v[140:143], v[2:5], v[240:255]
	v_exp_f32_e32 v76, v76
	v_exp_f32_e32 v77, v77
	v_exp_f32_e32 v78, v78
	v_exp_f32_e32 v79, v79
	s_waitcnt vmcnt(3) lgkmcnt(0)
	s_barrier
	s_andn2_b64 vcc, exec, s[2:3]
	s_cbranch_vccnz .LBB0_243
	s_waitcnt lgkmcnt(0)
	ds_read_b128 v[2:5], v0 offset:49248
	ds_read_b128 v[6:9], v0 offset:49216
	ds_read_b128 v[10:13], v0 offset:49184
	ds_read_b128 v[96:99], v0 offset:49152
	s_waitcnt lgkmcnt(3)
	v_pk_mul_f32 v[44:45], v[44:45], v[2:3]
	v_pk_mul_f32 v[236:237], v[236:237], v[2:3]
	s_waitcnt lgkmcnt(2)
	v_pk_mul_f32 v[40:41], v[40:41], v[6:7]
	v_pk_mul_f32 v[232:233], v[232:233], v[6:7]
	s_waitcnt lgkmcnt(1)
	v_pk_mul_f32 v[36:37], v[36:37], v[10:11]
	v_pk_mul_f32 v[228:229], v[228:229], v[10:11]
	v_pk_mul_f32 v[46:47], v[46:47], v[4:5]
	v_pk_mul_f32 v[238:239], v[238:239], v[4:5]
	v_pk_mul_f32 v[42:43], v[42:43], v[8:9]
	v_pk_mul_f32 v[234:235], v[234:235], v[8:9]
	v_pk_mul_f32 v[38:39], v[38:39], v[12:13]
	v_pk_mul_f32 v[230:231], v[230:231], v[12:13]
	s_waitcnt lgkmcnt(0)
	v_pk_mul_f32 v[34:35], v[34:35], v[98:99]
	v_pk_mul_f32 v[226:227], v[226:227], v[98:99]
	v_pk_mul_f32 v[32:33], v[32:33], v[96:97]
	v_pk_mul_f32 v[224:225], v[224:225], v[96:97]
	v_pk_mul_f32 v[28:29], v[28:29], v[2:3]
	v_pk_mul_f32 v[252:253], v[252:253], v[2:3]
	v_pk_mul_f32 v[24:25], v[24:25], v[6:7]
	v_pk_mul_f32 v[248:249], v[248:249], v[6:7]
	v_pk_mul_f32 v[20:21], v[20:21], v[10:11]
	v_pk_mul_f32 v[244:245], v[244:245], v[10:11]
	v_pk_mul_f32 v[30:31], v[30:31], v[4:5]
	v_pk_mul_f32 v[254:255], v[254:255], v[4:5]
	v_pk_mul_f32 v[26:27], v[26:27], v[8:9]
	v_pk_mul_f32 v[250:251], v[250:251], v[8:9]
	v_pk_mul_f32 v[22:23], v[22:23], v[12:13]
	v_pk_mul_f32 v[246:247], v[246:247], v[12:13]
	v_pk_mul_f32 v[18:19], v[18:19], v[98:99]
	v_pk_mul_f32 v[242:243], v[242:243], v[98:99]
	v_pk_mul_f32 v[16:17], v[16:17], v[96:97]
	v_pk_mul_f32 v[240:241], v[240:241], v[96:97]

.LBB0_259:
	s_waitcnt lgkmcnt(14)
	v_add_u32_e32 v65, s98, v220
	v_add_u32_e32 v65, 0xf000, v65
	ds_read_b64_tr_b16 v[66:67], v65 offset:24576
	ds_read_b64_tr_b16 v[68:69], v65 offset:25088
	ds_read_b64_tr_b16 v[70:71], v65 offset:28672
	ds_read_b64_tr_b16 v[72:73], v65 offset:29184
	ds_read_b64_tr_b16 v[74:75], v65 offset:25600
	ds_read_b64_tr_b16 v[76:77], v65 offset:26112
	ds_read_b64_tr_b16 v[88:89], v65 offset:29696
	ds_read_b64_tr_b16 v[90:91], v65 offset:30208
	ds_read_b64_tr_b16 v[92:93], v65 offset:26624
	ds_read_b64_tr_b16 v[94:95], v65 offset:27136
	ds_read_b64_tr_b16 v[200:201], v65 offset:30720
	ds_read_b64_tr_b16 v[202:203], v65 offset:31232
	v_mfma_f32_32x32x16_bf16 v[32:47], v[156:159], v[196:199], v[32:47]
	v_exp_f32_e32 v112, v112
	v_exp_f32_e32 v113, v113
	v_exp_f32_e32 v114, v114
	v_exp_f32_e32 v115, v115
	s_waitcnt lgkmcnt(12)
	v_mfma_f32_32x32x16_bf16 v[16:31], v[156:159], v[188:191], v[16:31]
	v_exp_f32_e32 v116, v116
	v_exp_f32_e32 v117, v117
	v_exp_f32_e32 v118, v118
	v_exp_f32_e32 v119, v119
	v_add_u32_e32 v64, s65, v219
	ds_read_b128 v[188:191], v64
	ds_read_b128 v[184:187], v64 offset:512
	s_waitcnt lgkmcnt(12)
	v_mfma_f32_32x32x16_bf16 v[32:47], v[152:155], v[192:195], v[32:47]
	v_exp_f32_e32 v120, v120
	v_exp_f32_e32 v121, v121
	v_exp_f32_e32 v122, v122
	v_exp_f32_e32 v123, v123
	ds_read_b128 v[180:183], v64 offset:2048
	ds_read_b128 v[176:179], v64 offset:2560
	s_waitcnt lgkmcnt(12)
	v_mfma_f32_32x32x16_bf16 v[16:31], v[152:155], v[84:87], v[16:31]
	v_exp_f32_e32 v124, v124
	v_exp_f32_e32 v125, v125
	v_exp_f32_e32 v126, v126
	v_exp_f32_e32 v127, v127
	ds_read_b128 v[172:175], v64 offset:4096
	ds_read_b128 v[168:171], v64 offset:4608
	s_waitcnt lgkmcnt(12)
	v_mfma_f32_32x32x16_bf16 v[32:47], v[148:151], v[80:83], v[32:47]
	v_exp_f32_e32 v96, v96
	v_exp_f32_e32 v97, v97
	v_exp_f32_e32 v98, v98
	v_exp_f32_e32 v99, v99
	ds_read_b128 v[164:167], v64 offset:6144
	ds_read_b128 v[160:163], v64 offset:6656
	s_waitcnt lgkmcnt(12)
	v_mfma_f32_32x32x16_bf16 v[16:31], v[148:151], v[10:13], v[16:31]
	v_exp_f32_e32 v100, v100
	v_exp_f32_e32 v101, v101
	v_exp_f32_e32 v102, v102
	v_exp_f32_e32 v103, v103
	s_waitcnt lgkmcnt(10)
	v_mfma_f32_32x32x16_bf16 v[32:47], v[140:143], v[6:9], v[32:47]
	v_exp_f32_e32 v104, v104
	v_exp_f32_e32 v105, v105
	v_exp_f32_e32 v106, v106
	v_exp_f32_e32 v107, v107
	s_waitcnt lgkmcnt(8)
	v_mfma_f32_32x32x16_bf16 v[16:31], v[140:143], v[2:5], v[16:31]
	ds_read_b64_tr_b16 v[2:3], v65 offset:27648
	ds_read_b64_tr_b16 v[4:5], v65 offset:28160
	ds_read_b64_tr_b16 v[6:7], v65 offset:31744
	ds_read_b64_tr_b16 v[8:9], v65 offset:32256
	s_waitcnt lgkmcnt(4)
	v_mfma_f32_32x32x16_bf16 v[224:239], v[156:159], v[66:69], v[224:239]
	v_mfma_f32_32x32x16_bf16 v[240:255], v[156:159], v[70:73], v[240:255]
	v_mfma_f32_32x32x16_bf16 v[224:239], v[152:155], v[74:77], v[224:239]
	v_mfma_f32_32x32x16_bf16 v[240:255], v[152:155], v[88:91], v[240:255]
	v_mfma_f32_32x32x16_bf16 v[224:239], v[148:151], v[92:95], v[224:239]
	v_mfma_f32_32x32x16_bf16 v[240:255], v[148:151], v[200:203], v[240:255]
	s_waitcnt lgkmcnt(2)
	v_mfma_f32_32x32x16_bf16 v[224:239], v[140:143], v[2:5], v[224:239]
	s_waitcnt lgkmcnt(0)
	v_mfma_f32_32x32x16_bf16 v[240:255], v[140:143], v[6:9], v[240:255]
	v_exp_f32_e32 v108, v108
	v_exp_f32_e32 v109, v109
	v_exp_f32_e32 v110, v110
	v_exp_f32_e32 v111, v111
	s_mov_b64 s[44:45], -1
	s_and_b64 vcc, exec, s[2:3]
	s_cbranch_vccz .LBB0_292
	s_add_i32 s44, s46, -2
	s_cmp_ge_u32 s44, s66
	s_mov_b64 s[44:45], -1
	s_cbranch_scc0 .LBB0_262
	s_waitcnt vmcnt(0) lgkmcnt(0)
	s_barrier
	s_mov_b64 s[44:45], 0

.LBB0_274:
	s_waitcnt lgkmcnt(14)
	v_add_u32_e32 v97, s98, v220
	v_add_u32_e32 v97, 0xf000, v97
	ds_read_b64_tr_b16 v[98:99], v97 offset:24576
	ds_read_b64_tr_b16 v[100:101], v97 offset:25088
	ds_read_b64_tr_b16 v[102:103], v97 offset:28672
	ds_read_b64_tr_b16 v[104:105], v97 offset:29184
	ds_read_b64_tr_b16 v[106:107], v97 offset:25600
	ds_read_b64_tr_b16 v[108:109], v97 offset:26112
	ds_read_b64_tr_b16 v[120:121], v97 offset:29696
	ds_read_b64_tr_b16 v[122:123], v97 offset:30208
	ds_read_b64_tr_b16 v[124:125], v97 offset:26624
	ds_read_b64_tr_b16 v[126:127], v97 offset:27136
	v_mfma_f32_32x32x16_bf16 v[32:47], v[156:159], v[200:203], v[32:47]
	v_exp_f32_e32 v80, v80
	v_exp_f32_e32 v81, v81
	v_exp_f32_e32 v82, v82
	v_exp_f32_e32 v83, v83
	s_waitcnt lgkmcnt(12)
	v_mfma_f32_32x32x16_bf16 v[16:31], v[156:159], v[196:199], v[16:31]
	v_exp_f32_e32 v84, v84
	v_exp_f32_e32 v85, v85
	v_exp_f32_e32 v86, v86
	v_exp_f32_e32 v87, v87
	v_cndmask_b32_e64 v96, 0, 1, s[48:49]
	v_cmp_ne_u32_e64 s[6:7], 1, v96
	s_andn2_b64 vcc, exec, s[48:49]
	v_add_u32_e32 v96, s64, v219
	s_cbranch_vccnz .LBB0_276
	ds_read_b128 v[188:191], v96
	ds_read_b128 v[184:187], v96 offset:512

.LBB0_282:
	s_waitcnt lgkmcnt(4)
	v_mfma_f32_32x32x16_bf16 v[16:31], v[148:151], v[10:13], v[16:31]
	v_exp_f32_e32 v68, v68
	v_exp_f32_e32 v69, v69
	v_exp_f32_e32 v70, v70
	v_exp_f32_e32 v71, v71
	s_waitcnt lgkmcnt(2)
	v_mfma_f32_32x32x16_bf16 v[32:47], v[140:143], v[6:9], v[32:47]
	v_exp_f32_e32 v72, v72
	v_exp_f32_e32 v73, v73
	v_exp_f32_e32 v74, v74
	v_exp_f32_e32 v75, v75
	s_waitcnt lgkmcnt(0)
	v_mfma_f32_32x32x16_bf16 v[16:31], v[140:143], v[2:5], v[16:31]
	ds_read_b64_tr_b16 v[2:3], v97 offset:30720
	ds_read_b64_tr_b16 v[4:5], v97 offset:31232
	ds_read_b64_tr_b16 v[6:7], v97 offset:27648
	ds_read_b64_tr_b16 v[8:9], v97 offset:28160
	ds_read_b64_tr_b16 v[10:11], v97 offset:31744
	ds_read_b64_tr_b16 v[12:13], v97 offset:32256
	s_waitcnt lgkmcnt(6)
	v_mfma_f32_32x32x16_bf16 v[224:239], v[156:159], v[98:101], v[224:239]
	v_mfma_f32_32x32x16_bf16 v[240:255], v[156:159], v[102:105], v[240:255]
	v_mfma_f32_32x32x16_bf16 v[224:239], v[152:155], v[106:109], v[224:239]
	v_mfma_f32_32x32x16_bf16 v[240:255], v[152:155], v[120:123], v[240:255]
	v_mfma_f32_32x32x16_bf16 v[224:239], v[148:151], v[124:127], v[224:239]
	s_waitcnt lgkmcnt(4)
	v_mfma_f32_32x32x16_bf16 v[240:255], v[148:151], v[2:5], v[240:255]
	s_waitcnt lgkmcnt(2)
	v_mfma_f32_32x32x16_bf16 v[224:239], v[140:143], v[6:9], v[224:239]
	s_waitcnt lgkmcnt(0)
	v_mfma_f32_32x32x16_bf16 v[240:255], v[140:143], v[10:13], v[240:255]
	v_exp_f32_e32 v76, v76
	v_exp_f32_e32 v77, v77
	v_exp_f32_e32 v78, v78
	v_exp_f32_e32 v79, v79
	s_mov_b64 s[6:7], -1
	s_and_b64 vcc, exec, s[44:45]
	s_cbranch_vccz .LBB0_294
	s_and_b64 vcc, exec, s[2:3]
	s_cbranch_vccz .LBB0_285
	s_waitcnt vmcnt(0) lgkmcnt(0)
	s_barrier
	s_mov_b64 s[6:7], 0

.LBB0_304:
	s_waitcnt lgkmcnt(14)
	v_add_u32_e32 v14, s98, v220
	v_add_u32_e32 v14, 0xf000, v14
	ds_read_b64_tr_b16 v[80:81], v14 offset:24576
	ds_read_b64_tr_b16 v[82:83], v14 offset:25088
	ds_read_b64_tr_b16 v[84:85], v14 offset:28672
	ds_read_b64_tr_b16 v[86:87], v14 offset:29184
	ds_read_b64_tr_b16 v[88:89], v14 offset:25600
	ds_read_b64_tr_b16 v[90:91], v14 offset:26112
	ds_read_b64_tr_b16 v[92:93], v14 offset:29696
	ds_read_b64_tr_b16 v[94:95], v14 offset:30208
	ds_read_b64_tr_b16 v[96:97], v14 offset:26624
	ds_read_b64_tr_b16 v[98:99], v14 offset:27136
	ds_read_b64_tr_b16 v[100:101], v14 offset:30720
	ds_read_b64_tr_b16 v[102:103], v14 offset:31232
	ds_read_b64_tr_b16 v[104:105], v14 offset:27648
	ds_read_b64_tr_b16 v[106:107], v14 offset:28160
	ds_read_b64_tr_b16 v[108:109], v14 offset:31744
	ds_read_b64_tr_b16 v[110:111], v14 offset:32256
	v_mfma_f32_32x32x16_bf16 v[32:47], v[156:159], v[192:195], v[32:47]
	v_exp_f32_e32 v64, v64
	v_exp_f32_e32 v65, v65
	v_exp_f32_e32 v66, v66
	v_exp_f32_e32 v67, v67
	s_waitcnt lgkmcnt(12)
	v_mfma_f32_32x32x16_bf16 v[16:31], v[156:159], v[124:127], v[16:31]
	v_exp_f32_e32 v68, v68
	v_exp_f32_e32 v69, v69
	v_exp_f32_e32 v70, v70
	v_exp_f32_e32 v71, v71
	s_waitcnt lgkmcnt(10)
	v_mfma_f32_32x32x16_bf16 v[32:47], v[152:155], v[120:123], v[32:47]
	v_exp_f32_e32 v72, v72
	v_exp_f32_e32 v73, v73
	v_exp_f32_e32 v74, v74
	v_exp_f32_e32 v75, v75
	s_waitcnt lgkmcnt(8)
	v_mfma_f32_32x32x16_bf16 v[16:31], v[152:155], v[116:119], v[16:31]
	v_exp_f32_e32 v76, v76
	v_exp_f32_e32 v77, v77
	v_exp_f32_e32 v78, v78
	v_exp_f32_e32 v79, v79
	s_waitcnt lgkmcnt(6)
	v_mfma_f32_32x32x16_bf16 v[32:47], v[148:151], v[112:115], v[32:47]
	v_exp_f32_e32 v48, v48
	v_exp_f32_e32 v49, v49
	v_exp_f32_e32 v50, v50
	v_exp_f32_e32 v51, v51
	s_waitcnt lgkmcnt(4)
	v_mfma_f32_32x32x16_bf16 v[16:31], v[148:151], v[10:13], v[16:31]
	v_exp_f32_e32 v52, v52
	v_exp_f32_e32 v53, v53
	v_exp_f32_e32 v54, v54
	v_exp_f32_e32 v55, v55
	s_waitcnt lgkmcnt(2)
	v_mfma_f32_32x32x16_bf16 v[32:47], v[140:143], v[6:9], v[32:47]
	v_exp_f32_e32 v56, v56
	v_exp_f32_e32 v57, v57
	v_exp_f32_e32 v58, v58
	v_exp_f32_e32 v59, v59
	s_waitcnt lgkmcnt(0)
	v_mfma_f32_32x32x16_bf16 v[16:31], v[140:143], v[2:5], v[16:31]
	s_waitcnt lgkmcnt(0)
	v_mfma_f32_32x32x16_bf16 v[224:239], v[156:159], v[80:83], v[224:239]
	v_mfma_f32_32x32x16_bf16 v[240:255], v[156:159], v[84:87], v[240:255]
	v_mfma_f32_32x32x16_bf16 v[224:239], v[152:155], v[88:91], v[224:239]
	v_mfma_f32_32x32x16_bf16 v[240:255], v[152:155], v[92:95], v[240:255]
	v_mfma_f32_32x32x16_bf16 v[224:239], v[148:151], v[96:99], v[224:239]
	v_mfma_f32_32x32x16_bf16 v[240:255], v[148:151], v[100:103], v[240:255]
	v_mfma_f32_32x32x16_bf16 v[224:239], v[140:143], v[104:107], v[224:239]
	v_mfma_f32_32x32x16_bf16 v[240:255], v[140:143], v[108:111], v[240:255]
	v_exp_f32_e32 v60, v60
	v_exp_f32_e32 v61, v61
	v_exp_f32_e32 v62, v62
	v_exp_f32_e32 v63, v63
	s_andn2_b64 vcc, exec, s[2:3]
	v_lshl_add_u32 v2, v214, 2, s60
	s_cbranch_vccnz .LBB0_306
	s_waitcnt lgkmcnt(0)
	ds_read_b128 v[4:7], v2 offset:49248
	ds_read_b128 v[8:11], v2 offset:49216
	ds_read_b128 v[12:15], v2 offset:49184
	ds_read_b128 v[80:83], v2 offset:49152
	s_waitcnt lgkmcnt(3)
	v_pk_mul_f32 v[46:47], v[46:47], v[6:7]
	v_pk_mul_f32 v[238:239], v[238:239], v[6:7]
	s_waitcnt lgkmcnt(2)
	v_pk_mul_f32 v[42:43], v[42:43], v[10:11]
	v_pk_mul_f32 v[234:235], v[234:235], v[10:11]
	s_waitcnt lgkmcnt(1)
	v_pk_mul_f32 v[38:39], v[38:39], v[14:15]
	v_pk_mul_f32 v[230:231], v[230:231], v[14:15]
	s_waitcnt lgkmcnt(0)
	v_pk_mul_f32 v[34:35], v[34:35], v[82:83]
	v_pk_mul_f32 v[226:227], v[226:227], v[82:83]
	v_pk_mul_f32 v[44:45], v[44:45], v[4:5]
	v_pk_mul_f32 v[236:237], v[236:237], v[4:5]
	v_pk_mul_f32 v[40:41], v[40:41], v[8:9]
	v_pk_mul_f32 v[232:233], v[232:233], v[8:9]
	v_pk_mul_f32 v[36:37], v[36:37], v[12:13]
	v_pk_mul_f32 v[228:229], v[228:229], v[12:13]
	v_pk_mul_f32 v[32:33], v[32:33], v[80:81]
	v_pk_mul_f32 v[224:225], v[224:225], v[80:81]
	v_pk_mul_f32 v[30:31], v[30:31], v[6:7]
	v_pk_mul_f32 v[254:255], v[254:255], v[6:7]
	v_pk_mul_f32 v[26:27], v[26:27], v[10:11]
	v_pk_mul_f32 v[250:251], v[250:251], v[10:11]
	v_pk_mul_f32 v[22:23], v[22:23], v[14:15]
	v_pk_mul_f32 v[246:247], v[246:247], v[14:15]
	v_pk_mul_f32 v[18:19], v[18:19], v[82:83]
	v_pk_mul_f32 v[242:243], v[242:243], v[82:83]
	v_pk_mul_f32 v[28:29], v[28:29], v[4:5]
	v_pk_mul_f32 v[252:253], v[252:253], v[4:5]
	v_pk_mul_f32 v[24:25], v[24:25], v[8:9]
	v_pk_mul_f32 v[248:249], v[248:249], v[8:9]
	v_pk_mul_f32 v[20:21], v[20:21], v[12:13]
	v_pk_mul_f32 v[244:245], v[244:245], v[12:13]
	v_pk_mul_f32 v[16:17], v[16:17], v[80:81]
	v_pk_mul_f32 v[240:241], v[240:241], v[80:81]

.LBB0_1718:
	s_waitcnt lgkmcnt(14)
	v_add_u32_e32 v15, s98, v221
	v_add_u32_e32 v15, 0xf000, v15
	ds_read_b64_tr_b16 v[68:69], v15 offset:24576
	ds_read_b64_tr_b16 v[70:71], v15 offset:25088
	ds_read_b64_tr_b16 v[72:73], v15 offset:28672
	ds_read_b64_tr_b16 v[74:75], v15 offset:29184
	ds_read_b64_tr_b16 v[76:77], v15 offset:25600
	ds_read_b64_tr_b16 v[78:79], v15 offset:26112
	ds_read_b64_tr_b16 v[88:89], v15 offset:29696
	ds_read_b64_tr_b16 v[90:91], v15 offset:30208
	ds_read_b64_tr_b16 v[92:93], v15 offset:26624
	ds_read_b64_tr_b16 v[94:95], v15 offset:27136
	ds_read_b64_tr_b16 v[164:165], v15 offset:30720
	ds_read_b64_tr_b16 v[166:167], v15 offset:31232
	ds_read_b64_tr_b16 v[168:169], v15 offset:27648
	ds_read_b64_tr_b16 v[170:171], v15 offset:28160
	v_mfma_f32_32x32x16_bf16 v[32:47], v[156:159], v[192:195], v[32:47]
	v_exp_f32_e32 v112, v112
	v_exp_f32_e32 v113, v113
	v_exp_f32_e32 v114, v114
	v_exp_f32_e32 v115, v115
	s_waitcnt lgkmcnt(12)
	v_mfma_f32_32x32x16_bf16 v[16:31], v[156:159], v[188:191], v[16:31]
	v_exp_f32_e32 v116, v116
	v_exp_f32_e32 v117, v117
	v_exp_f32_e32 v118, v118
	v_exp_f32_e32 v119, v119
	v_add_u32_e32 v0, s45, v220
	ds_read_b128 v[64:67], v0
	ds_read_b128 v[160:163], v0 offset:512
	s_waitcnt lgkmcnt(12)
	v_mfma_f32_32x32x16_bf16 v[32:47], v[152:155], v[184:187], v[32:47]
	v_exp_f32_e32 v120, v120
	v_exp_f32_e32 v121, v121
	v_exp_f32_e32 v122, v122
	v_exp_f32_e32 v123, v123
	ds_read_b128 v[192:195], v0 offset:2048
	ds_read_b128 v[184:187], v0 offset:2560
	s_waitcnt lgkmcnt(12)
	v_mfma_f32_32x32x16_bf16 v[16:31], v[152:155], v[84:87], v[16:31]
	v_exp_f32_e32 v124, v124
	v_exp_f32_e32 v125, v125
	v_exp_f32_e32 v126, v126
	v_exp_f32_e32 v127, v127
	ds_read_b128 v[188:191], v0 offset:4096
	ds_read_b128 v[176:179], v0 offset:4608
	s_waitcnt lgkmcnt(12)
	v_mfma_f32_32x32x16_bf16 v[32:47], v[148:151], v[80:83], v[32:47]
	v_exp_f32_e32 v96, v96
	v_exp_f32_e32 v97, v97
	v_exp_f32_e32 v98, v98
	v_exp_f32_e32 v99, v99
	ds_read_b128 v[180:183], v0 offset:6144
	ds_read_b128 v[172:175], v0 offset:6656
	s_waitcnt lgkmcnt(12)
	v_mfma_f32_32x32x16_bf16 v[16:31], v[148:151], v[10:13], v[16:31]
	v_exp_f32_e32 v100, v100
	v_exp_f32_e32 v101, v101
	v_exp_f32_e32 v102, v102
	v_exp_f32_e32 v103, v103
	s_waitcnt lgkmcnt(10)
	v_mfma_f32_32x32x16_bf16 v[32:47], v[140:143], v[6:9], v[32:47]
	v_exp_f32_e32 v104, v104
	v_exp_f32_e32 v105, v105
	v_exp_f32_e32 v106, v106
	v_exp_f32_e32 v107, v107
	s_waitcnt lgkmcnt(8)
	v_mfma_f32_32x32x16_bf16 v[16:31], v[140:143], v[2:5], v[16:31]
	ds_read_b64_tr_b16 v[2:3], v15 offset:31744
	ds_read_b64_tr_b16 v[4:5], v15 offset:32256
	s_waitcnt lgkmcnt(2)
	v_mfma_f32_32x32x16_bf16 v[224:239], v[156:159], v[68:71], v[224:239]
	v_mfma_f32_32x32x16_bf16 v[240:255], v[156:159], v[72:75], v[240:255]
	v_mfma_f32_32x32x16_bf16 v[224:239], v[152:155], v[76:79], v[224:239]
	v_mfma_f32_32x32x16_bf16 v[240:255], v[152:155], v[88:91], v[240:255]
	v_mfma_f32_32x32x16_bf16 v[224:239], v[148:151], v[92:95], v[224:239]
	v_mfma_f32_32x32x16_bf16 v[240:255], v[148:151], v[164:167], v[240:255]
	v_mfma_f32_32x32x16_bf16 v[224:239], v[140:143], v[168:171], v[224:239]
	s_waitcnt lgkmcnt(0)
	v_mfma_f32_32x32x16_bf16 v[240:255], v[140:143], v[2:5], v[240:255]
	v_exp_f32_e32 v108, v108
	v_exp_f32_e32 v109, v109
	v_exp_f32_e32 v110, v110
	v_exp_f32_e32 v111, v111
	s_waitcnt vmcnt(3) lgkmcnt(0)
	s_barrier
	s_andn2_b64 vcc, exec, s[2:3]
	v_add_u32_e32 v0, s60, v222
	s_cbranch_vccnz .LBB0_1720
	s_waitcnt lgkmcnt(0)
	ds_read_b128 v[2:5], v0 offset:49248
	ds_read_b128 v[6:9], v0 offset:49216
	ds_read_b128 v[10:13], v0 offset:49184
	ds_read_b128 v[68:71], v0 offset:49152
	s_waitcnt lgkmcnt(3)
	v_pk_mul_f32 v[44:45], v[44:45], v[2:3]
	v_pk_mul_f32 v[236:237], v[236:237], v[2:3]
	s_waitcnt lgkmcnt(2)
	v_pk_mul_f32 v[40:41], v[40:41], v[6:7]
	v_pk_mul_f32 v[232:233], v[232:233], v[6:7]
	s_waitcnt lgkmcnt(1)
	v_pk_mul_f32 v[36:37], v[36:37], v[10:11]
	v_pk_mul_f32 v[228:229], v[228:229], v[10:11]
	v_pk_mul_f32 v[46:47], v[46:47], v[4:5]
	v_pk_mul_f32 v[238:239], v[238:239], v[4:5]
	v_pk_mul_f32 v[42:43], v[42:43], v[8:9]
	v_pk_mul_f32 v[234:235], v[234:235], v[8:9]
	v_pk_mul_f32 v[38:39], v[38:39], v[12:13]
	v_pk_mul_f32 v[230:231], v[230:231], v[12:13]
	s_waitcnt lgkmcnt(0)
	v_pk_mul_f32 v[34:35], v[34:35], v[70:71]
	v_pk_mul_f32 v[226:227], v[226:227], v[70:71]
	v_pk_mul_f32 v[32:33], v[32:33], v[68:69]
	v_pk_mul_f32 v[224:225], v[224:225], v[68:69]
	v_pk_mul_f32 v[28:29], v[28:29], v[2:3]
	v_pk_mul_f32 v[252:253], v[252:253], v[2:3]
	v_pk_mul_f32 v[24:25], v[24:25], v[6:7]
	v_pk_mul_f32 v[248:249], v[248:249], v[6:7]
	v_pk_mul_f32 v[20:21], v[20:21], v[10:11]
	v_pk_mul_f32 v[244:245], v[244:245], v[10:11]
	v_pk_mul_f32 v[30:31], v[30:31], v[4:5]
	v_pk_mul_f32 v[254:255], v[254:255], v[4:5]
	v_pk_mul_f32 v[26:27], v[26:27], v[8:9]
	v_pk_mul_f32 v[250:251], v[250:251], v[8:9]
	v_pk_mul_f32 v[22:23], v[22:23], v[12:13]
	v_pk_mul_f32 v[246:247], v[246:247], v[12:13]
	v_pk_mul_f32 v[18:19], v[18:19], v[70:71]
	v_pk_mul_f32 v[242:243], v[242:243], v[70:71]
	v_pk_mul_f32 v[16:17], v[16:17], v[68:69]
	v_pk_mul_f32 v[240:241], v[240:241], v[68:69]

.LBB0_1721:
	s_waitcnt lgkmcnt(14)
	v_add_u32_e32 v15, s98, v221
	v_add_u32_e32 v15, 0xf000, v15
	ds_read_b64_tr_b16 v[96:97], v15 offset:24576
	ds_read_b64_tr_b16 v[98:99], v15 offset:25088
	ds_read_b64_tr_b16 v[100:101], v15 offset:28672
	ds_read_b64_tr_b16 v[102:103], v15 offset:29184
	ds_read_b64_tr_b16 v[104:105], v15 offset:25600
	ds_read_b64_tr_b16 v[106:107], v15 offset:26112
	ds_read_b64_tr_b16 v[108:109], v15 offset:29696
	ds_read_b64_tr_b16 v[110:111], v15 offset:30208
	ds_read_b64_tr_b16 v[120:121], v15 offset:26624
	ds_read_b64_tr_b16 v[122:123], v15 offset:27136
	ds_read_b64_tr_b16 v[124:125], v15 offset:30720
	ds_read_b64_tr_b16 v[126:127], v15 offset:31232
	ds_read_b64_tr_b16 v[192:193], v15 offset:27648
	ds_read_b64_tr_b16 v[194:195], v15 offset:28160
	v_mfma_f32_32x32x16_bf16 v[32:47], v[156:159], v[168:171], v[32:47]
	v_exp_f32_e32 v80, v80
	v_exp_f32_e32 v81, v81
	v_exp_f32_e32 v82, v82
	v_exp_f32_e32 v83, v83
	s_waitcnt lgkmcnt(12)
	v_mfma_f32_32x32x16_bf16 v[16:31], v[156:159], v[164:167], v[16:31]
	v_exp_f32_e32 v84, v84
	v_exp_f32_e32 v85, v85
	v_exp_f32_e32 v86, v86
	v_exp_f32_e32 v87, v87
	v_add_u32_e32 v14, s64, v220
	ds_read_b128 v[188:191], v14
	ds_read_b128 v[184:187], v14 offset:512
	s_waitcnt lgkmcnt(12)
	v_mfma_f32_32x32x16_bf16 v[32:47], v[152:155], v[160:163], v[32:47]
	v_exp_f32_e32 v88, v88
	v_exp_f32_e32 v89, v89
	v_exp_f32_e32 v90, v90
	v_exp_f32_e32 v91, v91
	ds_read_b128 v[180:183], v14 offset:2048
	ds_read_b128 v[176:179], v14 offset:2560
	s_waitcnt lgkmcnt(12)
	v_mfma_f32_32x32x16_bf16 v[16:31], v[152:155], v[116:119], v[16:31]
	v_exp_f32_e32 v92, v92
	v_exp_f32_e32 v93, v93
	v_exp_f32_e32 v94, v94
	v_exp_f32_e32 v95, v95
	ds_read_b128 v[172:175], v14 offset:4096
	ds_read_b128 v[168:171], v14 offset:4608
	s_waitcnt lgkmcnt(12)
	v_mfma_f32_32x32x16_bf16 v[32:47], v[148:151], v[112:115], v[32:47]
	v_exp_f32_e32 v64, v64
	v_exp_f32_e32 v65, v65
	v_exp_f32_e32 v66, v66
	v_exp_f32_e32 v67, v67
	ds_read_b128 v[164:167], v14 offset:6144
	ds_read_b128 v[160:163], v14 offset:6656
	s_waitcnt lgkmcnt(12)
	v_mfma_f32_32x32x16_bf16 v[16:31], v[148:151], v[10:13], v[16:31]
	v_exp_f32_e32 v68, v68
	v_exp_f32_e32 v69, v69
	v_exp_f32_e32 v70, v70
	v_exp_f32_e32 v71, v71
	s_waitcnt lgkmcnt(10)
	v_mfma_f32_32x32x16_bf16 v[32:47], v[140:143], v[6:9], v[32:47]
	v_exp_f32_e32 v72, v72
	v_exp_f32_e32 v73, v73
	v_exp_f32_e32 v74, v74
	v_exp_f32_e32 v75, v75
	s_waitcnt lgkmcnt(8)
	v_mfma_f32_32x32x16_bf16 v[16:31], v[140:143], v[2:5], v[16:31]
	ds_read_b64_tr_b16 v[2:3], v15 offset:31744
	ds_read_b64_tr_b16 v[4:5], v15 offset:32256
	s_waitcnt lgkmcnt(2)
	v_mfma_f32_32x32x16_bf16 v[224:239], v[156:159], v[96:99], v[224:239]
	v_mfma_f32_32x32x16_bf16 v[240:255], v[156:159], v[100:103], v[240:255]
	v_mfma_f32_32x32x16_bf16 v[224:239], v[152:155], v[104:107], v[224:239]
	v_mfma_f32_32x32x16_bf16 v[240:255], v[152:155], v[108:111], v[240:255]
	v_mfma_f32_32x32x16_bf16 v[224:239], v[148:151], v[120:123], v[224:239]
	v_mfma_f32_32x32x16_bf16 v[240:255], v[148:151], v[124:127], v[240:255]
	v_mfma_f32_32x32x16_bf16 v[224:239], v[140:143], v[192:195], v[224:239]
	s_waitcnt lgkmcnt(0)
	v_mfma_f32_32x32x16_bf16 v[240:255], v[140:143], v[2:5], v[240:255]
	v_exp_f32_e32 v76, v76
	v_exp_f32_e32 v77, v77
	v_exp_f32_e32 v78, v78
	v_exp_f32_e32 v79, v79
	s_waitcnt vmcnt(3) lgkmcnt(0)
	s_barrier
	s_andn2_b64 vcc, exec, s[2:3]
	s_cbranch_vccnz .LBB0_1723
	s_waitcnt lgkmcnt(0)
	ds_read_b128 v[2:5], v0 offset:49248
	ds_read_b128 v[6:9], v0 offset:49216
	ds_read_b128 v[10:13], v0 offset:49184
	ds_read_b128 v[96:99], v0 offset:49152
	s_waitcnt lgkmcnt(3)
	v_pk_mul_f32 v[44:45], v[44:45], v[2:3]
	v_pk_mul_f32 v[236:237], v[236:237], v[2:3]
	s_waitcnt lgkmcnt(2)
	v_pk_mul_f32 v[40:41], v[40:41], v[6:7]
	v_pk_mul_f32 v[232:233], v[232:233], v[6:7]
	s_waitcnt lgkmcnt(1)
	v_pk_mul_f32 v[36:37], v[36:37], v[10:11]
	v_pk_mul_f32 v[228:229], v[228:229], v[10:11]
	v_pk_mul_f32 v[46:47], v[46:47], v[4:5]
	v_pk_mul_f32 v[238:239], v[238:239], v[4:5]
	v_pk_mul_f32 v[42:43], v[42:43], v[8:9]
	v_pk_mul_f32 v[234:235], v[234:235], v[8:9]
	v_pk_mul_f32 v[38:39], v[38:39], v[12:13]
	v_pk_mul_f32 v[230:231], v[230:231], v[12:13]
	s_waitcnt lgkmcnt(0)
	v_pk_mul_f32 v[34:35], v[34:35], v[98:99]
	v_pk_mul_f32 v[226:227], v[226:227], v[98:99]
	v_pk_mul_f32 v[32:33], v[32:33], v[96:97]
	v_pk_mul_f32 v[224:225], v[224:225], v[96:97]
	v_pk_mul_f32 v[28:29], v[28:29], v[2:3]
	v_pk_mul_f32 v[252:253], v[252:253], v[2:3]
	v_pk_mul_f32 v[24:25], v[24:25], v[6:7]
	v_pk_mul_f32 v[248:249], v[248:249], v[6:7]
	v_pk_mul_f32 v[20:21], v[20:21], v[10:11]
	v_pk_mul_f32 v[244:245], v[244:245], v[10:11]
	v_pk_mul_f32 v[30:31], v[30:31], v[4:5]
	v_pk_mul_f32 v[254:255], v[254:255], v[4:5]
	v_pk_mul_f32 v[26:27], v[26:27], v[8:9]
	v_pk_mul_f32 v[250:251], v[250:251], v[8:9]
	v_pk_mul_f32 v[22:23], v[22:23], v[12:13]
	v_pk_mul_f32 v[246:247], v[246:247], v[12:13]
	v_pk_mul_f32 v[18:19], v[18:19], v[98:99]
	v_pk_mul_f32 v[242:243], v[242:243], v[98:99]
	v_pk_mul_f32 v[16:17], v[16:17], v[96:97]
	v_pk_mul_f32 v[240:241], v[240:241], v[96:97]

.LBB0_1739:
	s_waitcnt lgkmcnt(14)
	v_add_u32_e32 v65, s98, v221
	v_add_u32_e32 v65, 0xf000, v65
	ds_read_b64_tr_b16 v[66:67], v65 offset:24576
	ds_read_b64_tr_b16 v[68:69], v65 offset:25088
	ds_read_b64_tr_b16 v[70:71], v65 offset:28672
	ds_read_b64_tr_b16 v[72:73], v65 offset:29184
	ds_read_b64_tr_b16 v[74:75], v65 offset:25600
	ds_read_b64_tr_b16 v[76:77], v65 offset:26112
	ds_read_b64_tr_b16 v[88:89], v65 offset:29696
	ds_read_b64_tr_b16 v[90:91], v65 offset:30208
	ds_read_b64_tr_b16 v[92:93], v65 offset:26624
	ds_read_b64_tr_b16 v[94:95], v65 offset:27136
	ds_read_b64_tr_b16 v[200:201], v65 offset:30720
	ds_read_b64_tr_b16 v[202:203], v65 offset:31232
	v_mfma_f32_32x32x16_bf16 v[32:47], v[156:159], v[196:199], v[32:47]
	v_exp_f32_e32 v112, v112
	v_exp_f32_e32 v113, v113
	v_exp_f32_e32 v114, v114
	v_exp_f32_e32 v115, v115
	s_waitcnt lgkmcnt(12)
	v_mfma_f32_32x32x16_bf16 v[16:31], v[156:159], v[188:191], v[16:31]
	v_exp_f32_e32 v116, v116
	v_exp_f32_e32 v117, v117
	v_exp_f32_e32 v118, v118
	v_exp_f32_e32 v119, v119
	v_add_u32_e32 v64, s65, v220
	ds_read_b128 v[188:191], v64
	ds_read_b128 v[184:187], v64 offset:512
	s_waitcnt lgkmcnt(12)
	v_mfma_f32_32x32x16_bf16 v[32:47], v[152:155], v[192:195], v[32:47]
	v_exp_f32_e32 v120, v120
	v_exp_f32_e32 v121, v121
	v_exp_f32_e32 v122, v122
	v_exp_f32_e32 v123, v123
	ds_read_b128 v[180:183], v64 offset:2048
	ds_read_b128 v[176:179], v64 offset:2560
	s_waitcnt lgkmcnt(12)
	v_mfma_f32_32x32x16_bf16 v[16:31], v[152:155], v[84:87], v[16:31]
	v_exp_f32_e32 v124, v124
	v_exp_f32_e32 v125, v125
	v_exp_f32_e32 v126, v126
	v_exp_f32_e32 v127, v127
	ds_read_b128 v[172:175], v64 offset:4096
	ds_read_b128 v[168:171], v64 offset:4608
	s_waitcnt lgkmcnt(12)
	v_mfma_f32_32x32x16_bf16 v[32:47], v[148:151], v[80:83], v[32:47]
	v_exp_f32_e32 v96, v96
	v_exp_f32_e32 v97, v97
	v_exp_f32_e32 v98, v98
	v_exp_f32_e32 v99, v99
	ds_read_b128 v[164:167], v64 offset:6144
	ds_read_b128 v[160:163], v64 offset:6656
	s_waitcnt lgkmcnt(12)
	v_mfma_f32_32x32x16_bf16 v[16:31], v[148:151], v[10:13], v[16:31]
	v_exp_f32_e32 v100, v100
	v_exp_f32_e32 v101, v101
	v_exp_f32_e32 v102, v102
	v_exp_f32_e32 v103, v103
	s_waitcnt lgkmcnt(10)
	v_mfma_f32_32x32x16_bf16 v[32:47], v[140:143], v[6:9], v[32:47]
	v_exp_f32_e32 v104, v104
	v_exp_f32_e32 v105, v105
	v_exp_f32_e32 v106, v106
	v_exp_f32_e32 v107, v107
	s_waitcnt lgkmcnt(8)
	v_mfma_f32_32x32x16_bf16 v[16:31], v[140:143], v[2:5], v[16:31]
	ds_read_b64_tr_b16 v[2:3], v65 offset:27648
	ds_read_b64_tr_b16 v[4:5], v65 offset:28160
	ds_read_b64_tr_b16 v[6:7], v65 offset:31744
	ds_read_b64_tr_b16 v[8:9], v65 offset:32256
	s_waitcnt lgkmcnt(4)
	v_mfma_f32_32x32x16_bf16 v[224:239], v[156:159], v[66:69], v[224:239]
	v_mfma_f32_32x32x16_bf16 v[240:255], v[156:159], v[70:73], v[240:255]
	v_mfma_f32_32x32x16_bf16 v[224:239], v[152:155], v[74:77], v[224:239]
	v_mfma_f32_32x32x16_bf16 v[240:255], v[152:155], v[88:91], v[240:255]
	v_mfma_f32_32x32x16_bf16 v[224:239], v[148:151], v[92:95], v[224:239]
	v_mfma_f32_32x32x16_bf16 v[240:255], v[148:151], v[200:203], v[240:255]
	s_waitcnt lgkmcnt(2)
	v_mfma_f32_32x32x16_bf16 v[224:239], v[140:143], v[2:5], v[224:239]
	s_waitcnt lgkmcnt(0)
	v_mfma_f32_32x32x16_bf16 v[240:255], v[140:143], v[6:9], v[240:255]
	v_exp_f32_e32 v108, v108
	v_exp_f32_e32 v109, v109
	v_exp_f32_e32 v110, v110
	v_exp_f32_e32 v111, v111
	s_mov_b64 s[44:45], -1
	s_and_b64 vcc, exec, s[2:3]
	s_cbranch_vccz .LBB0_1772
	s_add_i32 s44, s46, -2
	s_cmp_ge_u32 s44, s66
	s_mov_b64 s[44:45], -1
	s_cbranch_scc0 .LBB0_1742
	s_waitcnt vmcnt(0) lgkmcnt(0)
	s_barrier
	s_mov_b64 s[44:45], 0

.LBB0_1754:
	s_waitcnt lgkmcnt(14)
	v_add_u32_e32 v97, s98, v221
	v_add_u32_e32 v97, 0xf000, v97
	ds_read_b64_tr_b16 v[98:99], v97 offset:24576
	ds_read_b64_tr_b16 v[100:101], v97 offset:25088
	ds_read_b64_tr_b16 v[102:103], v97 offset:28672
	ds_read_b64_tr_b16 v[104:105], v97 offset:29184
	ds_read_b64_tr_b16 v[106:107], v97 offset:25600
	ds_read_b64_tr_b16 v[108:109], v97 offset:26112
	ds_read_b64_tr_b16 v[120:121], v97 offset:29696
	ds_read_b64_tr_b16 v[122:123], v97 offset:30208
	ds_read_b64_tr_b16 v[124:125], v97 offset:26624
	ds_read_b64_tr_b16 v[126:127], v97 offset:27136
	v_mfma_f32_32x32x16_bf16 v[32:47], v[156:159], v[200:203], v[32:47]
	v_exp_f32_e32 v80, v80
	v_exp_f32_e32 v81, v81
	v_exp_f32_e32 v82, v82
	v_exp_f32_e32 v83, v83
	s_waitcnt lgkmcnt(12)
	v_mfma_f32_32x32x16_bf16 v[16:31], v[156:159], v[196:199], v[16:31]
	v_exp_f32_e32 v84, v84
	v_exp_f32_e32 v85, v85
	v_exp_f32_e32 v86, v86
	v_exp_f32_e32 v87, v87
	v_cndmask_b32_e64 v96, 0, 1, s[48:49]
	v_cmp_ne_u32_e64 s[6:7], 1, v96
	s_andn2_b64 vcc, exec, s[48:49]
	v_add_u32_e32 v96, s64, v220
	s_cbranch_vccnz .LBB0_1756
	ds_read_b128 v[188:191], v96
	ds_read_b128 v[184:187], v96 offset:512

.LBB0_1784:
	s_waitcnt lgkmcnt(14)
	v_add_u32_e32 v14, s98, v221
	v_add_u32_e32 v14, 0xf000, v14
	ds_read_b64_tr_b16 v[80:81], v14 offset:24576
	ds_read_b64_tr_b16 v[82:83], v14 offset:25088
	ds_read_b64_tr_b16 v[84:85], v14 offset:28672
	ds_read_b64_tr_b16 v[86:87], v14 offset:29184
	ds_read_b64_tr_b16 v[88:89], v14 offset:25600
	ds_read_b64_tr_b16 v[90:91], v14 offset:26112
	ds_read_b64_tr_b16 v[92:93], v14 offset:29696
	ds_read_b64_tr_b16 v[94:95], v14 offset:30208
	ds_read_b64_tr_b16 v[96:97], v14 offset:26624
	ds_read_b64_tr_b16 v[98:99], v14 offset:27136
	ds_read_b64_tr_b16 v[100:101], v14 offset:30720
	ds_read_b64_tr_b16 v[102:103], v14 offset:31232
	ds_read_b64_tr_b16 v[104:105], v14 offset:27648
	ds_read_b64_tr_b16 v[106:107], v14 offset:28160
	ds_read_b64_tr_b16 v[108:109], v14 offset:31744
	ds_read_b64_tr_b16 v[110:111], v14 offset:32256
	v_mfma_f32_32x32x16_bf16 v[32:47], v[156:159], v[192:195], v[32:47]
	v_exp_f32_e32 v64, v64
	v_exp_f32_e32 v65, v65
	v_exp_f32_e32 v66, v66
	v_exp_f32_e32 v67, v67
	s_waitcnt lgkmcnt(12)
	v_mfma_f32_32x32x16_bf16 v[16:31], v[156:159], v[124:127], v[16:31]
	v_exp_f32_e32 v68, v68
	v_exp_f32_e32 v69, v69
	v_exp_f32_e32 v70, v70
	v_exp_f32_e32 v71, v71
	s_waitcnt lgkmcnt(10)
	v_mfma_f32_32x32x16_bf16 v[32:47], v[152:155], v[120:123], v[32:47]
	v_exp_f32_e32 v72, v72
	v_exp_f32_e32 v73, v73
	v_exp_f32_e32 v74, v74
	v_exp_f32_e32 v75, v75
	s_waitcnt lgkmcnt(8)
	v_mfma_f32_32x32x16_bf16 v[16:31], v[152:155], v[116:119], v[16:31]
	v_exp_f32_e32 v76, v76
	v_exp_f32_e32 v77, v77
	v_exp_f32_e32 v78, v78
	v_exp_f32_e32 v79, v79
	s_waitcnt lgkmcnt(6)
	v_mfma_f32_32x32x16_bf16 v[32:47], v[148:151], v[112:115], v[32:47]
	v_exp_f32_e32 v48, v48
	v_exp_f32_e32 v49, v49
	v_exp_f32_e32 v50, v50
	v_exp_f32_e32 v51, v51
	s_waitcnt lgkmcnt(4)
	v_mfma_f32_32x32x16_bf16 v[16:31], v[148:151], v[10:13], v[16:31]
	v_exp_f32_e32 v52, v52
	v_exp_f32_e32 v53, v53
	v_exp_f32_e32 v54, v54
	v_exp_f32_e32 v55, v55
	s_waitcnt lgkmcnt(2)
	v_mfma_f32_32x32x16_bf16 v[32:47], v[140:143], v[6:9], v[32:47]
	v_exp_f32_e32 v56, v56
	v_exp_f32_e32 v57, v57
	v_exp_f32_e32 v58, v58
	v_exp_f32_e32 v59, v59
	s_waitcnt lgkmcnt(0)
	v_mfma_f32_32x32x16_bf16 v[16:31], v[140:143], v[2:5], v[16:31]
	s_waitcnt lgkmcnt(0)
	v_mfma_f32_32x32x16_bf16 v[224:239], v[156:159], v[80:83], v[224:239]
	v_mfma_f32_32x32x16_bf16 v[240:255], v[156:159], v[84:87], v[240:255]
	v_mfma_f32_32x32x16_bf16 v[224:239], v[152:155], v[88:91], v[224:239]
	v_mfma_f32_32x32x16_bf16 v[240:255], v[152:155], v[92:95], v[240:255]
	v_mfma_f32_32x32x16_bf16 v[224:239], v[148:151], v[96:99], v[224:239]
	v_mfma_f32_32x32x16_bf16 v[240:255], v[148:151], v[100:103], v[240:255]
	v_mfma_f32_32x32x16_bf16 v[224:239], v[140:143], v[104:107], v[224:239]
	v_mfma_f32_32x32x16_bf16 v[240:255], v[140:143], v[108:111], v[240:255]
	v_exp_f32_e32 v60, v60
	v_exp_f32_e32 v61, v61
	v_exp_f32_e32 v62, v62
	v_exp_f32_e32 v63, v63
	s_andn2_b64 vcc, exec, s[2:3]
	v_lshl_add_u32 v2, v215, 2, s60
	s_cbranch_vccnz .LBB0_1786
	s_waitcnt lgkmcnt(0)
	ds_read_b128 v[4:7], v2 offset:49248
	ds_read_b128 v[8:11], v2 offset:49216
	ds_read_b128 v[12:15], v2 offset:49184
	ds_read_b128 v[80:83], v2 offset:49152
	s_waitcnt lgkmcnt(3)
	v_pk_mul_f32 v[46:47], v[46:47], v[6:7]
	v_pk_mul_f32 v[238:239], v[238:239], v[6:7]
	s_waitcnt lgkmcnt(2)
	v_pk_mul_f32 v[42:43], v[42:43], v[10:11]
	v_pk_mul_f32 v[234:235], v[234:235], v[10:11]
	s_waitcnt lgkmcnt(1)
	v_pk_mul_f32 v[38:39], v[38:39], v[14:15]
	v_pk_mul_f32 v[230:231], v[230:231], v[14:15]
	s_waitcnt lgkmcnt(0)
	v_pk_mul_f32 v[34:35], v[34:35], v[82:83]
	v_pk_mul_f32 v[226:227], v[226:227], v[82:83]
	v_pk_mul_f32 v[44:45], v[44:45], v[4:5]
	v_pk_mul_f32 v[236:237], v[236:237], v[4:5]
	v_pk_mul_f32 v[40:41], v[40:41], v[8:9]
	v_pk_mul_f32 v[232:233], v[232:233], v[8:9]
	v_pk_mul_f32 v[36:37], v[36:37], v[12:13]
	v_pk_mul_f32 v[228:229], v[228:229], v[12:13]
	v_pk_mul_f32 v[32:33], v[32:33], v[80:81]
	v_pk_mul_f32 v[224:225], v[224:225], v[80:81]
	v_pk_mul_f32 v[30:31], v[30:31], v[6:7]
	v_pk_mul_f32 v[254:255], v[254:255], v[6:7]
	v_pk_mul_f32 v[26:27], v[26:27], v[10:11]
	v_pk_mul_f32 v[250:251], v[250:251], v[10:11]
	v_pk_mul_f32 v[22:23], v[22:23], v[14:15]
	v_pk_mul_f32 v[246:247], v[246:247], v[14:15]
	v_pk_mul_f32 v[18:19], v[18:19], v[82:83]
	v_pk_mul_f32 v[242:243], v[242:243], v[82:83]
	v_pk_mul_f32 v[28:29], v[28:29], v[4:5]
	v_pk_mul_f32 v[252:253], v[252:253], v[4:5]
	v_pk_mul_f32 v[24:25], v[24:25], v[8:9]
	v_pk_mul_f32 v[248:249], v[248:249], v[8:9]
	v_pk_mul_f32 v[20:21], v[20:21], v[12:13]
	v_pk_mul_f32 v[244:245], v[244:245], v[12:13]
	v_pk_mul_f32 v[16:17], v[16:17], v[80:81]
	v_pk_mul_f32 v[240:241], v[240:241], v[80:81]
